# rms / final-norm phases: whole-line row stores marked non-temporal (nt)
# speedup vs baseline: 1.0004x; 1.0004x over previous
; __device__ __forceinline__ void rms_row(const f32x4 (&v)[4], const float* g, int lane, float& rs, f32x4 (&y)[4]) {
;     float s = 0.f;
; #pragma unroll
;     for (int j = 0; j < 4; ++j) s += (v[j].x * v[j].x + v[j].y * v[j].y) + (v[j].z * v[j].z + v[j].w * v[j].w);
;     rs = __builtin_amdgcn_rsqf(wave_sum(s) * (1.f / DM) + EPS);
; #pragma unroll
;     for (int j = 0; j < 4; ++j) { const f32x4 gv = *((const f32x4*)g + lane + 64 * j); y[j] = v[j] * rs * gv; }
; }
; __device__ __forceinline__ void load_bf16_row(const bf16* row, int lane, f32x4 (&v)[4]) {
;     const u32x2* p = (const u32x2*)row + lane;
; #pragma unroll
;     for (int j = 0; j < 4; ++j) { const u32x2 w = p[64 * j]; v[j] = (f32x4){bflo(w.x), bfhi(w.x), bflo(w.y), bfhi(w.y)}; }
; template <int NSLICE> __device__ __forceinline__ void rms_phase(ArgP a, const float* g, bool final_out, int G) {
;     ...
;     for (int m = gw; m < R_META; m += 2 * NGW) {
;         const int m2 = m + NGW; const bool has2 = m2 < R_META;
;         f32x4 v[4], u[4];
;         load_bf16_row(H + (size_t)m * DM, lane, v); load_bf16_row(H + (size_t)(has2 ? m2 : m) * DM, lane, u);
;         float rs; f32x4 y[4];
;         rms_row(v, g, lane, rs, y);
;         if (!final_out) store_bf16_row(XN + (size_t)m * DM, lane, y);
;         else { float* o = a->out + O_YP + (size_t)m * DM;
; #pragma unroll
;             for (int j = 0; j < 4; ++j) *((f32x4*)o + lane + 64 * j) = y[j]; }
.LBB0_1317:
	v_ashrrev_i32_e32 v37, 31, v36
	v_lshlrev_b64 v[0:1], 11, v[36:37]
	v_lshl_add_u64 v[0:1], v[20:21], 0, v[0:1]
	global_load_dwordx2 v[2:3], v[0:1], off
	global_load_dwordx2 v[6:7], v[0:1], off offset:512
	global_load_dwordx2 v[10:11], v[0:1], off offset:1024
	s_nop 0
	global_load_dwordx2 v[0:1], v[0:1], off offset:1536
	v_add_u32_e32 v26, s38, v36
	s_movk_i32 s14, 0x4000
	v_cmp_gt_i32_e32 vcc, s14, v26
	s_waitcnt vmcnt(0)
	v_lshlrev_b32_e32 v39, 16, v0
	v_and_b32_e32 v15, 0xffff0000, v0
	v_cndmask_b32_e32 v0, v36, v26, vcc
	v_lshlrev_b32_e32 v12, 16, v1
	v_and_b32_e32 v13, 0xffff0000, v1
	v_ashrrev_i32_e32 v1, 31, v0
	v_lshlrev_b64 v[0:1], 11, v[0:1]
	v_lshl_add_u64 v[0:1], v[20:21], 0, v[0:1]
	global_load_dwordx2 v[32:33], v[0:1], off
	global_load_dwordx2 v[30:31], v[0:1], off offset:512
	global_load_dwordx2 v[28:29], v[0:1], off offset:1024
	global_load_dwordx2 v[34:35], v[0:1], off offset:1536
	v_lshlrev_b32_e32 v0, 16, v2
	v_and_b32_e32 v1, 0xffff0000, v2
	v_lshlrev_b32_e32 v2, 16, v3
	v_and_b32_e32 v3, 0xffff0000, v3
	v_mul_f32_e32 v4, v3, v3
	v_pk_fma_f32 v[48:49], v[2:3], v[2:3], v[4:5] op_sel_hi:[1,1,0]
	v_lshlrev_b32_e32 v5, 16, v7
	v_lshlrev_b32_e32 v4, 16, v6
	v_and_b32_e32 v7, 0xffff0000, v7
	v_and_b32_e32 v6, 0xffff0000, v6
	v_mul_f32_e32 v14, v1, v1
	v_pk_mul_f32 v[8:9], v[6:7], v[6:7]
	v_pk_fma_f32 v[52:53], v[0:1], v[0:1], v[14:15] op_sel_hi:[1,1,0]
	v_pk_fma_f32 v[50:51], v[4:5], v[4:5], v[8:9]
	v_mov_b32_e32 v38, v52
	v_mov_b32_e32 v54, v48
	v_mov_b32_e32 v55, v39
	v_and_b32_e32 v9, 0xffff0000, v10
	v_mul_f32_e32 v17, v15, v15
	v_pk_add_f32 v[48:49], v[52:53], v[48:49]
	v_pk_mul_f32 v[52:53], v[38:39], v[54:55]
	v_pk_add_f32 v[50:51], v[50:51], v[50:51] op_sel:[0,1] op_sel_hi:[1,0]
	v_lshlrev_b32_e32 v8, 16, v10
	v_lshlrev_b32_e32 v10, 16, v11
	v_and_b32_e32 v11, 0xffff0000, v11
	v_mov_b32_e32 v49, v53
	v_mov_b32_e32 v51, v17
	v_mul_f32_e32 v14, v9, v9
	v_pk_add_f32 v[48:49], v[48:49], v[50:51]
	v_pk_fma_f32 v[50:51], v[8:9], v[8:9], v[14:15] op_sel_hi:[1,1,0]
	v_mul_f32_e32 v14, v11, v11
	v_mul_f32_e32 v27, v12, v12
	v_mul_f32_e32 v47, v13, v13
	v_pk_fma_f32 v[52:53], v[10:11], v[10:11], v[14:15] op_sel_hi:[1,1,0]
	v_mov_b32_e32 v51, v27
	v_mov_b32_e32 v53, v47
	v_pk_add_f32 v[50:51], v[50:51], v[52:53]
	v_mov_b32_e32 v52, v4
	v_pk_add_f32 v[48:49], v[48:49], v[50:51]
	v_mov_b32_e32 v53, v6
	v_add_f32_e32 v14, v48, v49
	global_load_dwordx4 v[48:51], v[22:23], off
	ds_bpermute_b32 v17, v41, v14
	v_mov_b32_e32 v6, v5
	v_lshlrev_b64 v[36:37], 12, v[36:37]
	v_lshl_add_u64 v[36:37], v[24:25], 0, v[36:37]
	s_waitcnt lgkmcnt(0)
	v_add_f32_e32 v14, v14, v17
	ds_bpermute_b32 v17, v42, v14
	s_waitcnt lgkmcnt(0)
	v_add_f32_e32 v14, v14, v17
	ds_bpermute_b32 v17, v43, v14
	s_waitcnt lgkmcnt(0)
	v_add_f32_e32 v14, v14, v17
	ds_bpermute_b32 v17, v44, v14
	s_waitcnt lgkmcnt(0)
	v_add_f32_e32 v14, v14, v17
	ds_bpermute_b32 v17, v45, v14
	s_waitcnt lgkmcnt(0)
	v_add_f32_e32 v14, v14, v17
	ds_bpermute_b32 v17, v46, v14
	s_waitcnt lgkmcnt(0)
	v_add_f32_e32 v14, v14, v17
	v_fmamk_f32 v14, v14, 0x3a800000, v207
	v_rsq_f32_e32 v38, v14
	v_mov_b32_e32 v14, v39
	v_pk_mul_f32 v[0:1], v[38:39], v[0:1] op_sel_hi:[0,1]
	v_pk_mul_f32 v[2:3], v[38:39], v[2:3] op_sel_hi:[0,1]
	v_pk_mul_f32 v[52:53], v[38:39], v[52:53] op_sel_hi:[0,1]
	v_pk_mul_f32 v[4:5], v[38:39], v[6:7] op_sel_hi:[0,1]
	v_pk_mul_f32 v[8:9], v[38:39], v[8:9] op_sel_hi:[0,1]
	v_pk_mul_f32 v[10:11], v[38:39], v[10:11] op_sel_hi:[0,1]
	v_pk_mul_f32 v[12:13], v[38:39], v[12:13] op_sel_hi:[0,1]
	s_waitcnt vmcnt(0)
	v_pk_mul_f32 v[2:3], v[50:51], v[2:3]
	v_pk_mul_f32 v[0:1], v[48:49], v[0:1]
	global_load_dwordx4 v[48:51], v[22:23], off offset:1024
	s_waitcnt vmcnt(0)
	v_pk_mul_f32 v[6:7], v[50:51], v[4:5]
	v_pk_mul_f32 v[4:5], v[48:49], v[52:53]
	global_load_dwordx4 v[48:51], v[22:23], off offset:2048
	v_pk_mul_f32 v[52:53], v[38:39], v[14:15] op_sel_hi:[0,1]
	s_waitcnt vmcnt(0)
	v_pk_mul_f32 v[10:11], v[50:51], v[10:11]
	v_pk_mul_f32 v[8:9], v[48:49], v[8:9]
	global_load_dwordx4 v[48:51], v[22:23], off offset:3072
	s_waitcnt vmcnt(0)
	v_pk_mul_f32 v[14:15], v[50:51], v[12:13]
	v_pk_mul_f32 v[12:13], v[48:49], v[52:53]
	global_store_dwordx4 v[36:37], v[0:3], off nt
	global_store_dwordx4 v[36:37], v[4:7], off offset:1024 nt
	global_store_dwordx4 v[36:37], v[8:11], off offset:2048 nt
	global_store_dwordx4 v[36:37], v[12:15], off offset:3072 nt
	s_and_saveexec_b64 s[14:15], vcc
	s_cbranch_execz .LBB0_1316
; __device__ __forceinline__ void rms_row(const f32x4 (&v)[4], const float* g, int lane, float& rs, f32x4 (&y)[4]) {
;     float s = 0.f;
; #pragma unroll
;     for (int j = 0; j < 4; ++j) s += (v[j].x * v[j].x + v[j].y * v[j].y) + (v[j].z * v[j].z + v[j].w * v[j].w);
;     rs = __builtin_amdgcn_rsqf(wave_sum(s) * (1.f / DM) + EPS);
; #pragma unroll
;     for (int j = 0; j < 4; ++j) { const f32x4 gv = *((const f32x4*)g + lane + 64 * j); y[j] = v[j] * rs * gv; }
; }
; __device__ __forceinline__ void load_bf16_row(const bf16* row, int lane, f32x4 (&v)[4]) {
;     const u32x2* p = (const u32x2*)row + lane;
; #pragma unroll
;     for (int j = 0; j < 4; ++j) { const u32x2 w = p[64 * j]; v[j] = (f32x4){bflo(w.x), bfhi(w.x), bflo(w.y), bfhi(w.y)}; }
; template <int NSLICE> __device__ __forceinline__ void rms_phase(ArgP a, const float* g, bool final_out, int G) {
;     ...
;         if (has2) {
;             rms_row(u, g, lane, rs, y);
;             if (!final_out) store_bf16_row(XN + (size_t)m2 * DM, lane, y);
;             else { float* o = a->out + O_YP + (size_t)m2 * DM;
; #pragma unroll
;                 for (int j = 0; j < 4; ++j) *((f32x4*)o + lane + 64 * j) = y[j]; }
;         }
	v_lshlrev_b32_e32 v37, 16, v34
	v_and_b32_e32 v15, 0xffff0000, v34
	v_lshlrev_b32_e32 v12, 16, v35
	v_and_b32_e32 v13, 0xffff0000, v35
	v_lshlrev_b32_e32 v34, 16, v32
	v_and_b32_e32 v35, 0xffff0000, v32
	v_lshlrev_b32_e32 v32, 16, v33
	v_and_b32_e32 v33, 0xffff0000, v33
	v_mul_f32_e32 v0, v33, v33
	v_and_b32_e32 v7, 0xffff0000, v31
	v_and_b32_e32 v6, 0xffff0000, v30
	v_mul_f32_e32 v14, v35, v35
	v_pk_fma_f32 v[0:1], v[32:33], v[32:33], v[0:1] op_sel_hi:[1,1,0]
	v_lshlrev_b32_e32 v5, 16, v31
	v_lshlrev_b32_e32 v4, 16, v30
	v_pk_mul_f32 v[2:3], v[6:7], v[6:7]
	v_lshlrev_b32_e32 v8, 16, v28
	v_and_b32_e32 v9, 0xffff0000, v28
	v_lshlrev_b32_e32 v10, 16, v29
	v_and_b32_e32 v11, 0xffff0000, v29
	v_pk_fma_f32 v[28:29], v[34:35], v[34:35], v[14:15] op_sel_hi:[1,1,0]
	v_pk_fma_f32 v[2:3], v[4:5], v[4:5], v[2:3]
	v_mov_b32_e32 v36, v28
	v_mov_b32_e32 v30, v0
	v_mov_b32_e32 v31, v37
	v_mul_f32_e32 v17, v15, v15
	v_pk_add_f32 v[0:1], v[28:29], v[0:1]
	v_pk_mul_f32 v[28:29], v[36:37], v[30:31]
	v_pk_add_f32 v[2:3], v[2:3], v[2:3] op_sel:[0,1] op_sel_hi:[1,0]
	v_mov_b32_e32 v1, v29
	v_mov_b32_e32 v3, v17
	v_pk_add_f32 v[0:1], v[0:1], v[2:3]
	v_mul_f32_e32 v2, v9, v9
	v_mul_f32_e32 v14, v11, v11
	v_mul_f32_e32 v27, v12, v12
	v_mul_f32_e32 v38, v13, v13
	v_pk_fma_f32 v[2:3], v[8:9], v[8:9], v[2:3] op_sel_hi:[1,1,0]
	v_pk_fma_f32 v[28:29], v[10:11], v[10:11], v[14:15] op_sel_hi:[1,1,0]
	v_mov_b32_e32 v3, v27
	v_mov_b32_e32 v29, v38
	v_pk_add_f32 v[2:3], v[2:3], v[28:29]
	v_mov_b32_e32 v14, v37
	v_pk_add_f32 v[0:1], v[0:1], v[2:3]
	v_ashrrev_i32_e32 v27, 31, v26
	v_add_f32_e32 v0, v0, v1
	ds_bpermute_b32 v1, v41, v0
	s_waitcnt lgkmcnt(0)
	v_add_f32_e32 v0, v0, v1
	ds_bpermute_b32 v1, v42, v0
	s_waitcnt lgkmcnt(0)
	v_add_f32_e32 v0, v0, v1
	ds_bpermute_b32 v1, v43, v0
	s_waitcnt lgkmcnt(0)
	v_add_f32_e32 v0, v0, v1
	ds_bpermute_b32 v1, v44, v0
	s_waitcnt lgkmcnt(0)
	v_add_f32_e32 v0, v0, v1
	ds_bpermute_b32 v1, v45, v0
	s_waitcnt lgkmcnt(0)
	v_add_f32_e32 v0, v0, v1
	ds_bpermute_b32 v1, v46, v0
	s_waitcnt lgkmcnt(0)
	v_add_f32_e32 v0, v0, v1
	v_fmamk_f32 v0, v0, 0x3a800000, v207
	v_rsq_f32_e32 v28, v0
	global_load_dwordx4 v[0:3], v[22:23], off
	v_pk_mul_f32 v[30:31], v[28:29], v[34:35] op_sel_hi:[0,1]
	v_pk_mul_f32 v[32:33], v[28:29], v[32:33] op_sel_hi:[0,1]
	v_mov_b32_e32 v34, v4
	v_mov_b32_e32 v35, v6
	v_mov_b32_e32 v6, v5
	v_pk_mul_f32 v[34:35], v[28:29], v[34:35] op_sel_hi:[0,1]
	v_pk_mul_f32 v[4:5], v[28:29], v[6:7] op_sel_hi:[0,1]
	v_pk_mul_f32 v[8:9], v[28:29], v[8:9] op_sel_hi:[0,1]
	v_pk_mul_f32 v[10:11], v[28:29], v[10:11] op_sel_hi:[0,1]
	v_pk_mul_f32 v[12:13], v[28:29], v[12:13] op_sel_hi:[0,1]
	s_waitcnt vmcnt(0)
	v_pk_mul_f32 v[2:3], v[2:3], v[32:33]
	v_pk_mul_f32 v[0:1], v[0:1], v[30:31]
	global_load_dwordx4 v[30:33], v[22:23], off offset:1024
	s_waitcnt vmcnt(0)
	v_pk_mul_f32 v[6:7], v[32:33], v[4:5]
	v_pk_mul_f32 v[4:5], v[30:31], v[34:35]
	global_load_dwordx4 v[30:33], v[22:23], off offset:2048
	v_pk_mul_f32 v[34:35], v[28:29], v[14:15] op_sel_hi:[0,1]
	v_lshlrev_b64 v[28:29], 12, v[26:27]
	v_lshl_add_u64 v[28:29], v[24:25], 0, v[28:29]
	s_waitcnt vmcnt(0)
	v_pk_mul_f32 v[10:11], v[32:33], v[10:11]
	v_pk_mul_f32 v[8:9], v[30:31], v[8:9]
	global_load_dwordx4 v[30:33], v[22:23], off offset:3072
	s_waitcnt vmcnt(0)
	v_pk_mul_f32 v[14:15], v[32:33], v[12:13]
	v_pk_mul_f32 v[12:13], v[30:31], v[34:35]
	global_store_dwordx4 v[28:29], v[0:3], off nt
	global_store_dwordx4 v[28:29], v[4:7], off offset:1024 nt
	global_store_dwordx4 v[28:29], v[8:11], off offset:2048 nt
	global_store_dwordx4 v[28:29], v[12:15], off offset:3072 nt
	s_branch .LBB0_1316

; __device__ __forceinline__ void load_bf16_row(const bf16* row, int lane, f32x4 (&v)[4]) {
;     const u32x2* p = (const u32x2*)row + lane;
; #pragma unroll
;     for (int j = 0; j < 4; ++j) { const u32x2 w = p[64 * j]; v[j] = (f32x4){bflo(w.x), bfhi(w.x), bflo(w.y), bfhi(w.y)}; }
; }
; template <int NSLICE> __device__ __forceinline__ void rms_phase(ArgP a, const float* g, bool final_out, int G) {
;     ...
;     for (int t = (NGW - 1 - gw); t < M_REAL - R_META; t += NGW) {
;         const int m = R_META + t;
;         if (final_out && m < R_SAMP) continue;
;         f32x4 v[4]; load_bf16_row(H + (size_t)m * DM, lane, v);
;         const bf16* PART = (const bf16*)(a->ws + WS_P + 6 * ROWBUF) + (size_t)t * DM;
; #pragma unroll
;         for (int sl = 0; sl < NSLICE; ++sl) {
;             f32x4 pv[4]; load_bf16_row(PART + (size_t)sl * (MP - R_META) * DM, lane, pv);
; #pragma unroll
;             for (int j = 0; j < 4; ++j) v[j] = v[j] + pv[j];
;         }
.LBB0_1328:
	v_add_u32_e32 v0, 0xffffc000, v188
	s_movk_i32 s8, 0x7f
	v_cmp_lt_i32_e32 vcc, s8, v0
	s_and_saveexec_b64 s[8:9], vcc
	s_cbranch_execz .LBB0_1327
	v_mov_b32_e32 v1, v189
	v_lshlrev_b64 v[2:3], 11, v[188:189]
	v_lshlrev_b64 v[0:1], 11, v[0:1]
	v_lshl_add_u64 v[2:3], v[12:13], 0, v[2:3]
	v_lshl_add_u64 v[0:1], v[14:15], 0, v[0:1]
	global_load_dwordx2 v[4:5], v[2:3], off
	global_load_dwordx2 v[8:9], v[2:3], off offset:512
	global_load_dwordx2 v[20:21], v[2:3], off offset:1024
	global_load_dwordx2 v[26:27], v[0:1], off
	global_load_dwordx2 v[30:31], v[0:1], off offset:512
	global_load_dwordx2 v[34:35], v[0:1], off offset:1024
	global_load_dwordx2 v[38:39], v[0:1], off offset:1536
	s_mov_b32 s10, 0x280000
	global_load_dwordx2 v[2:3], v[2:3], off offset:1536
	v_mov_b32_e32 v19, v189
	s_waitcnt vmcnt(0)
	v_lshlrev_b32_e32 v6, 16, v4
	v_and_b32_e32 v7, 0xffff0000, v4
	v_lshlrev_b32_e32 v4, 16, v5
	v_and_b32_e32 v5, 0xffff0000, v5
	v_lshlrev_b32_e32 v28, 16, v26
	v_and_b32_e32 v29, 0xffff0000, v26
	v_lshlrev_b32_e32 v26, 16, v27
	v_and_b32_e32 v27, 0xffff0000, v27
	v_pk_add_f32 v[4:5], v[4:5], v[26:27]
	v_add_co_u32_e32 v26, vcc, s10, v0
	v_lshlrev_b32_e32 v10, 16, v8
	v_and_b32_e32 v11, 0xffff0000, v8
	v_lshlrev_b32_e32 v22, 16, v20
	v_and_b32_e32 v23, 0xffff0000, v20
	v_lshlrev_b32_e32 v32, 16, v30
	v_and_b32_e32 v33, 0xffff0000, v30
	v_lshlrev_b32_e32 v36, 16, v34
	v_and_b32_e32 v37, 0xffff0000, v34
	v_addc_co_u32_e32 v27, vcc, 0, v1, vcc
	v_pk_add_f32 v[6:7], v[6:7], v[28:29]
	v_pk_add_f32 v[10:11], v[10:11], v[32:33]
	v_pk_add_f32 v[22:23], v[22:23], v[36:37]
	global_load_dwordx2 v[28:29], v[26:27], off
	global_load_dwordx2 v[32:33], v[26:27], off offset:512
	global_load_dwordx2 v[36:37], v[26:27], off offset:1024
	v_lshlrev_b32_e32 v8, 16, v9
	global_load_dwordx2 v[26:27], v[26:27], off offset:1536
	v_and_b32_e32 v9, 0xffff0000, v9
	v_lshlrev_b32_e32 v24, 16, v2
	v_and_b32_e32 v25, 0xffff0000, v2
	v_lshlrev_b32_e32 v2, 16, v3
	v_and_b32_e32 v3, 0xffff0000, v3
	v_lshlrev_b32_e32 v30, 16, v31
	v_and_b32_e32 v31, 0xffff0000, v31
	v_lshlrev_b32_e32 v40, 16, v38
	v_and_b32_e32 v41, 0xffff0000, v38
	v_lshlrev_b32_e32 v38, 16, v39
	v_and_b32_e32 v39, 0xffff0000, v39
	v_pk_add_f32 v[8:9], v[8:9], v[30:31]
	v_pk_add_f32 v[2:3], v[2:3], v[38:39]
	v_pk_add_f32 v[24:25], v[24:25], v[40:41]
	s_mov_b32 s10, 0x500000
	v_lshlrev_b32_e32 v20, 16, v21
	v_and_b32_e32 v21, 0xffff0000, v21
	v_lshlrev_b32_e32 v34, 16, v35
	v_and_b32_e32 v35, 0xffff0000, v35
	v_pk_add_f32 v[20:21], v[20:21], v[34:35]
	s_waitcnt vmcnt(3)
	v_lshlrev_b32_e32 v30, 16, v28
	v_and_b32_e32 v31, 0xffff0000, v28
	v_lshlrev_b32_e32 v28, 16, v29
	v_and_b32_e32 v29, 0xffff0000, v29
	s_waitcnt vmcnt(0)
	v_lshlrev_b32_e32 v40, 16, v26
	v_and_b32_e32 v41, 0xffff0000, v26
	v_lshlrev_b32_e32 v26, 16, v27
	v_and_b32_e32 v27, 0xffff0000, v27
	v_pk_add_f32 v[28:29], v[4:5], v[28:29]
	v_pk_add_f32 v[4:5], v[6:7], v[30:31]
	v_pk_add_f32 v[30:31], v[24:25], v[40:41]
	v_pk_add_f32 v[24:25], v[2:3], v[26:27]
	v_add_co_u32_e32 v2, vcc, s10, v0
	v_lshlrev_b32_e32 v34, 16, v32
	v_and_b32_e32 v35, 0xffff0000, v32
	v_lshlrev_b32_e32 v32, 16, v33
	v_and_b32_e32 v33, 0xffff0000, v33
	v_lshlrev_b32_e32 v38, 16, v36
	v_and_b32_e32 v39, 0xffff0000, v36
	v_lshlrev_b32_e32 v36, 16, v37
	v_and_b32_e32 v37, 0xffff0000, v37
	v_addc_co_u32_e32 v3, vcc, 0, v1, vcc
	v_pk_add_f32 v[8:9], v[8:9], v[32:33]
	v_pk_add_f32 v[6:7], v[10:11], v[34:35]
	v_pk_add_f32 v[10:11], v[22:23], v[38:39]
	v_pk_add_f32 v[22:23], v[20:21], v[36:37]
	global_load_dwordx2 v[20:21], v[2:3], off
	global_load_dwordx2 v[32:33], v[2:3], off offset:512
	global_load_dwordx2 v[36:37], v[2:3], off offset:1024
	s_mov_b32 s10, 0x780000
	global_load_dwordx2 v[2:3], v[2:3], off offset:1536
	s_waitcnt vmcnt(3)
	v_lshlrev_b32_e32 v26, 16, v20
	v_and_b32_e32 v27, 0xffff0000, v20
	v_lshlrev_b32_e32 v20, 16, v21
	v_and_b32_e32 v21, 0xffff0000, v21
	s_waitcnt vmcnt(2)
	v_lshlrev_b32_e32 v34, 16, v32
	v_and_b32_e32 v35, 0xffff0000, v32
	v_lshlrev_b32_e32 v32, 16, v33
	v_and_b32_e32 v33, 0xffff0000, v33
	s_waitcnt vmcnt(1)
	v_lshlrev_b32_e32 v38, 16, v36
	v_and_b32_e32 v39, 0xffff0000, v36
	v_lshlrev_b32_e32 v36, 16, v37
	v_and_b32_e32 v37, 0xffff0000, v37
	s_waitcnt vmcnt(0)
	v_lshlrev_b32_e32 v40, 16, v2
	v_and_b32_e32 v41, 0xffff0000, v2
	v_lshlrev_b32_e32 v42, 16, v3
	v_and_b32_e32 v43, 0xffff0000, v3
	v_pk_add_f32 v[2:3], v[28:29], v[20:21]
	v_pk_add_f32 v[20:21], v[8:9], v[32:33]
	v_pk_add_f32 v[8:9], v[22:23], v[36:37]
	v_pk_add_f32 v[22:23], v[10:11], v[38:39]
	v_add_co_u32_e32 v10, vcc, s10, v0
	v_pk_add_f32 v[4:5], v[4:5], v[26:27]
	s_nop 0
	v_addc_co_u32_e32 v11, vcc, 0, v1, vcc
	global_load_dwordx2 v[28:29], v[10:11], off
	global_load_dwordx2 v[32:33], v[10:11], off offset:512
	global_load_dwordx2 v[36:37], v[10:11], off offset:1024
	v_pk_add_f32 v[6:7], v[6:7], v[34:35]
	global_load_dwordx2 v[10:11], v[10:11], off offset:1536
	v_pk_add_f32 v[26:27], v[30:31], v[40:41]
	s_mov_b32 s10, 0xa00000
	v_pk_add_f32 v[24:25], v[24:25], v[42:43]
	s_waitcnt vmcnt(3)
	v_lshlrev_b32_e32 v30, 16, v28
	v_and_b32_e32 v31, 0xffff0000, v28
	s_waitcnt vmcnt(2)
	v_lshlrev_b32_e32 v34, 16, v32
	v_and_b32_e32 v35, 0xffff0000, v32
	v_lshlrev_b32_e32 v32, 16, v33
	v_and_b32_e32 v33, 0xffff0000, v33
	s_waitcnt vmcnt(1)
	v_lshlrev_b32_e32 v38, 16, v36
	v_and_b32_e32 v39, 0xffff0000, v36
	v_lshlrev_b32_e32 v36, 16, v37
	v_and_b32_e32 v37, 0xffff0000, v37
	s_waitcnt vmcnt(0)
; template <int NSLICE> __device__ __forceinline__ void rms_phase(ArgP a, const float* g, bool final_out, int G) {
;     ...
;         const bf16* PART = (const bf16*)(a->ws + WS_P + 6 * ROWBUF) + (size_t)t * DM;
; #pragma unroll
;         for (int sl = 0; sl < NSLICE; ++sl) {
;             f32x4 pv[4]; load_bf16_row(PART + (size_t)sl * (MP - R_META) * DM, lane, pv);
; #pragma unroll
;             for (int j = 0; j < 4; ++j) v[j] = v[j] + pv[j];
;         }
	v_lshlrev_b32_e32 v40, 16, v10
	v_and_b32_e32 v41, 0xffff0000, v10
	v_lshlrev_b32_e32 v42, 16, v11
	v_and_b32_e32 v43, 0xffff0000, v11
	v_pk_add_f32 v[10:11], v[4:5], v[30:31]
	v_pk_add_f32 v[4:5], v[20:21], v[32:33]
	v_pk_add_f32 v[20:21], v[6:7], v[34:35]
	v_pk_add_f32 v[6:7], v[22:23], v[38:39]
	v_pk_add_f32 v[22:23], v[8:9], v[36:37]
	v_pk_add_f32 v[8:9], v[26:27], v[40:41]
	v_add_co_u32_e32 v26, vcc, s10, v0
	v_lshlrev_b32_e32 v28, 16, v29
	v_and_b32_e32 v29, 0xffff0000, v29
	v_addc_co_u32_e32 v27, vcc, 0, v1, vcc
	v_pk_add_f32 v[2:3], v[2:3], v[28:29]
	global_load_dwordx2 v[28:29], v[26:27], off
	global_load_dwordx2 v[32:33], v[26:27], off offset:512
	global_load_dwordx2 v[36:37], v[26:27], off offset:1024
	v_pk_add_f32 v[24:25], v[24:25], v[42:43]
	global_load_dwordx2 v[26:27], v[26:27], off offset:1536
	s_mov_b32 s10, 0xc80000
	s_waitcnt vmcnt(3)
	v_lshlrev_b32_e32 v30, 16, v28
	v_and_b32_e32 v31, 0xffff0000, v28
	v_lshlrev_b32_e32 v28, 16, v29
	v_and_b32_e32 v29, 0xffff0000, v29
	s_waitcnt vmcnt(2)
	v_lshlrev_b32_e32 v34, 16, v32
	v_and_b32_e32 v35, 0xffff0000, v32
	v_lshlrev_b32_e32 v32, 16, v33
	v_and_b32_e32 v33, 0xffff0000, v33
	s_waitcnt vmcnt(1)
	v_lshlrev_b32_e32 v38, 16, v36
	v_and_b32_e32 v39, 0xffff0000, v36
	v_lshlrev_b32_e32 v36, 16, v37
	v_and_b32_e32 v37, 0xffff0000, v37
	s_waitcnt vmcnt(0)
	v_lshlrev_b32_e32 v40, 16, v26
	v_and_b32_e32 v41, 0xffff0000, v26
	v_lshlrev_b32_e32 v42, 16, v27
	v_and_b32_e32 v43, 0xffff0000, v27
	v_pk_add_f32 v[26:27], v[2:3], v[28:29]
	v_pk_add_f32 v[2:3], v[20:21], v[34:35]
	v_pk_add_f32 v[20:21], v[4:5], v[32:33]
	v_pk_add_f32 v[4:5], v[22:23], v[36:37]
	v_pk_add_f32 v[22:23], v[6:7], v[38:39]
	v_pk_add_f32 v[6:7], v[24:25], v[42:43]
	v_pk_add_f32 v[24:25], v[8:9], v[40:41]
	v_add_co_u32_e32 v8, vcc, s10, v0
	v_pk_add_f32 v[10:11], v[10:11], v[30:31]
	s_nop 0
	v_addc_co_u32_e32 v9, vcc, 0, v1, vcc
	global_load_dwordx2 v[28:29], v[8:9], off
	global_load_dwordx2 v[32:33], v[8:9], off offset:512
	global_load_dwordx2 v[36:37], v[8:9], off offset:1024
	s_mov_b32 s10, 0xf00000
	global_load_dwordx2 v[8:9], v[8:9], off offset:1536
	s_waitcnt vmcnt(3)
	v_lshlrev_b32_e32 v30, 16, v28
	v_and_b32_e32 v31, 0xffff0000, v28
	v_lshlrev_b32_e32 v28, 16, v29
	v_and_b32_e32 v29, 0xffff0000, v29
	s_waitcnt vmcnt(2)
	v_lshlrev_b32_e32 v34, 16, v32
	v_and_b32_e32 v35, 0xffff0000, v32
	v_lshlrev_b32_e32 v32, 16, v33
	v_and_b32_e32 v33, 0xffff0000, v33
	s_waitcnt vmcnt(1)
	v_lshlrev_b32_e32 v38, 16, v36
	v_and_b32_e32 v39, 0xffff0000, v36
	v_lshlrev_b32_e32 v36, 16, v37
	v_and_b32_e32 v37, 0xffff0000, v37
	s_waitcnt vmcnt(0)
	v_lshlrev_b32_e32 v40, 16, v8
	v_and_b32_e32 v41, 0xffff0000, v8
	v_lshlrev_b32_e32 v42, 16, v9
	v_and_b32_e32 v43, 0xffff0000, v9
	v_pk_add_f32 v[8:9], v[26:27], v[28:29]
	v_pk_add_f32 v[26:27], v[10:11], v[30:31]
	v_pk_add_f32 v[10:11], v[20:21], v[32:33]
	v_pk_add_f32 v[20:21], v[2:3], v[34:35]
	v_pk_add_f32 v[2:3], v[22:23], v[38:39]
	v_pk_add_f32 v[22:23], v[4:5], v[36:37]
	v_pk_add_f32 v[4:5], v[24:25], v[40:41]
	v_add_co_u32_e32 v24, vcc, s10, v0
	v_pk_add_f32 v[6:7], v[6:7], v[42:43]
	s_nop 0
	v_addc_co_u32_e32 v25, vcc, 0, v1, vcc
	global_load_dwordx2 v[28:29], v[24:25], off
	global_load_dwordx2 v[32:33], v[24:25], off offset:512
	global_load_dwordx2 v[36:37], v[24:25], off offset:1024
	s_mov_b32 s10, 0x1180000
	global_load_dwordx2 v[24:25], v[24:25], off offset:1536
	s_waitcnt vmcnt(3)
	v_lshlrev_b32_e32 v30, 16, v28
	v_and_b32_e32 v31, 0xffff0000, v28
	v_lshlrev_b32_e32 v28, 16, v29
	v_and_b32_e32 v29, 0xffff0000, v29
	s_waitcnt vmcnt(0)
	v_lshlrev_b32_e32 v40, 16, v24
	v_and_b32_e32 v41, 0xffff0000, v24
	v_lshlrev_b32_e32 v24, 16, v25
	v_and_b32_e32 v25, 0xffff0000, v25
	v_pk_add_f32 v[6:7], v[6:7], v[24:25]
	v_add_co_u32_e32 v24, vcc, s10, v0
	v_lshlrev_b32_e32 v34, 16, v32
	v_and_b32_e32 v35, 0xffff0000, v32
	v_lshlrev_b32_e32 v32, 16, v33
	v_and_b32_e32 v33, 0xffff0000, v33
	v_lshlrev_b32_e32 v38, 16, v36
	v_and_b32_e32 v39, 0xffff0000, v36
	v_lshlrev_b32_e32 v36, 16, v37
	v_and_b32_e32 v37, 0xffff0000, v37
	v_addc_co_u32_e32 v25, vcc, 0, v1, vcc
	v_pk_add_f32 v[8:9], v[8:9], v[28:29]
	v_pk_add_f32 v[10:11], v[10:11], v[32:33]
	v_pk_add_f32 v[22:23], v[22:23], v[36:37]
	global_load_dwordx2 v[28:29], v[24:25], off
	global_load_dwordx2 v[32:33], v[24:25], off offset:512
	global_load_dwordx2 v[36:37], v[24:25], off offset:1024
	v_pk_add_f32 v[4:5], v[4:5], v[40:41]
	global_load_dwordx2 v[24:25], v[24:25], off offset:1536
	s_mov_b32 s10, 0x1400000
	v_pk_add_f32 v[26:27], v[26:27], v[30:31]
	v_pk_add_f32 v[20:21], v[20:21], v[34:35]
	v_pk_add_f32 v[2:3], v[2:3], v[38:39]
	s_waitcnt vmcnt(3)
	v_lshlrev_b32_e32 v30, 16, v28
	v_and_b32_e32 v31, 0xffff0000, v28
	v_lshlrev_b32_e32 v28, 16, v29
	v_and_b32_e32 v29, 0xffff0000, v29
	s_waitcnt vmcnt(0)
	v_lshlrev_b32_e32 v40, 16, v24
	v_and_b32_e32 v41, 0xffff0000, v24
	v_lshlrev_b32_e32 v24, 16, v25
	v_and_b32_e32 v25, 0xffff0000, v25
	v_pk_add_f32 v[6:7], v[6:7], v[24:25]
	v_add_co_u32_e32 v24, vcc, s10, v0
	v_lshlrev_b32_e32 v34, 16, v32
	v_and_b32_e32 v35, 0xffff0000, v32
	v_lshlrev_b32_e32 v32, 16, v33
	v_and_b32_e32 v33, 0xffff0000, v33
	v_lshlrev_b32_e32 v38, 16, v36
	v_and_b32_e32 v39, 0xffff0000, v36
	v_lshlrev_b32_e32 v36, 16, v37
	v_and_b32_e32 v37, 0xffff0000, v37
	v_addc_co_u32_e32 v25, vcc, 0, v1, vcc
	v_pk_add_f32 v[8:9], v[8:9], v[28:29]
	v_pk_add_f32 v[10:11], v[10:11], v[32:33]
	v_pk_add_f32 v[22:23], v[22:23], v[36:37]
	global_load_dwordx2 v[28:29], v[24:25], off
	global_load_dwordx2 v[32:33], v[24:25], off offset:512
	global_load_dwordx2 v[36:37], v[24:25], off offset:1024
	v_pk_add_f32 v[20:21], v[20:21], v[34:35]
	global_load_dwordx2 v[24:25], v[24:25], off offset:1536
	v_pk_add_f32 v[4:5], v[4:5], v[40:41]
	s_mov_b32 s10, 0x1680000
	v_pk_add_f32 v[26:27], v[26:27], v[30:31]
	v_pk_add_f32 v[2:3], v[2:3], v[38:39]
	s_waitcnt vmcnt(3)
; template <int NSLICE> __device__ __forceinline__ void rms_phase(ArgP a, const float* g, bool final_out, int G) {
;     ...
;         const bf16* PART = (const bf16*)(a->ws + WS_P + 6 * ROWBUF) + (size_t)t * DM;
; #pragma unroll
;         for (int sl = 0; sl < NSLICE; ++sl) {
;             f32x4 pv[4]; load_bf16_row(PART + (size_t)sl * (MP - R_META) * DM, lane, pv);
; #pragma unroll
;             for (int j = 0; j < 4; ++j) v[j] = v[j] + pv[j];
;         }
	v_lshlrev_b32_e32 v30, 16, v28
	s_waitcnt vmcnt(2)
	v_lshlrev_b32_e32 v34, 16, v32
	v_and_b32_e32 v35, 0xffff0000, v32
	v_lshlrev_b32_e32 v32, 16, v33
	v_and_b32_e32 v33, 0xffff0000, v33
	s_waitcnt vmcnt(0)
	v_lshlrev_b32_e32 v40, 16, v24
	v_and_b32_e32 v41, 0xffff0000, v24
	v_pk_add_f32 v[10:11], v[10:11], v[32:33]
	v_pk_add_f32 v[32:33], v[4:5], v[40:41]
	v_add_co_u32_e32 v4, vcc, s10, v0
	v_and_b32_e32 v31, 0xffff0000, v28
	v_lshlrev_b32_e32 v28, 16, v29
	v_and_b32_e32 v29, 0xffff0000, v29
	v_lshlrev_b32_e32 v24, 16, v25
	v_and_b32_e32 v25, 0xffff0000, v25
	v_addc_co_u32_e32 v5, vcc, 0, v1, vcc
	v_pk_add_f32 v[8:9], v[8:9], v[28:29]
	v_pk_add_f32 v[28:29], v[20:21], v[34:35]
	v_pk_add_f32 v[6:7], v[6:7], v[24:25]
	global_load_dwordx2 v[20:21], v[4:5], off
	global_load_dwordx2 v[24:25], v[4:5], off offset:512
	v_lshlrev_b32_e32 v38, 16, v36
	v_and_b32_e32 v39, 0xffff0000, v36
	v_lshlrev_b32_e32 v36, 16, v37
	v_and_b32_e32 v37, 0xffff0000, v37
	v_pk_add_f32 v[26:27], v[26:27], v[30:31]
	v_pk_add_f32 v[30:31], v[22:23], v[36:37]
	s_mov_b32 s10, 0x1900000
	v_pk_add_f32 v[2:3], v[2:3], v[38:39]
	s_waitcnt vmcnt(1)
	v_lshlrev_b32_e32 v22, 16, v20
	s_waitcnt vmcnt(0)
	v_lshlrev_b32_e32 v34, 16, v24
	v_and_b32_e32 v35, 0xffff0000, v24
	v_lshlrev_b32_e32 v36, 16, v25
	v_and_b32_e32 v37, 0xffff0000, v25
	global_load_dwordx2 v[24:25], v[4:5], off offset:1024
	v_and_b32_e32 v23, 0xffff0000, v20
	v_lshlrev_b32_e32 v20, 16, v21
	v_and_b32_e32 v21, 0xffff0000, v21
	v_pk_add_f32 v[20:21], v[8:9], v[20:21]
	v_pk_add_f32 v[8:9], v[10:11], v[36:37]
	v_add_co_u32_e32 v36, vcc, s10, v0
	s_load_dwordx2 s[10:11], s[0:1], 0x78
	s_nop 0
	v_addc_co_u32_e32 v37, vcc, 0, v1, vcc
	global_load_dwordx2 v[0:1], v[36:37], off
	s_waitcnt vmcnt(1)
	v_lshlrev_b32_e32 v38, 16, v24
	global_load_dwordx2 v[4:5], v[4:5], off offset:1536
	v_and_b32_e32 v39, 0xffff0000, v24
	v_lshlrev_b32_e32 v40, 16, v25
	v_and_b32_e32 v41, 0xffff0000, v25
	v_pk_add_f32 v[24:25], v[26:27], v[22:23]
	v_pk_add_f32 v[22:23], v[28:29], v[34:35]
	global_load_dwordx2 v[28:29], v[36:37], off offset:512
	global_load_dwordx2 v[34:35], v[36:37], off offset:1024
	v_pk_add_f32 v[10:11], v[30:31], v[40:41]
	global_load_dwordx2 v[36:37], v[36:37], off offset:1536
	s_waitcnt vmcnt(4)
	v_lshlrev_b32_e32 v26, 16, v0
	v_and_b32_e32 v27, 0xffff0000, v0
	v_lshlrev_b32_e32 v0, 16, v1
	v_and_b32_e32 v1, 0xffff0000, v1
	v_pk_add_f32 v[0:1], v[20:21], v[0:1]
	s_waitcnt vmcnt(3)
	v_lshlrev_b32_e32 v42, 16, v4
	v_and_b32_e32 v43, 0xffff0000, v4
	v_lshlrev_b32_e32 v44, 16, v5
	v_and_b32_e32 v45, 0xffff0000, v5
	v_pk_add_f32 v[4:5], v[2:3], v[38:39]
	v_pk_add_f32 v[2:3], v[32:33], v[42:43]
	s_waitcnt vmcnt(2)
	v_lshlrev_b32_e32 v30, 16, v28
	v_and_b32_e32 v31, 0xffff0000, v28
	v_lshlrev_b32_e32 v28, 16, v29
	v_and_b32_e32 v29, 0xffff0000, v29
	s_waitcnt vmcnt(1)
	v_lshlrev_b32_e32 v32, 16, v34
	v_and_b32_e32 v33, 0xffff0000, v34
	v_lshlrev_b32_e32 v34, 16, v35
	v_and_b32_e32 v35, 0xffff0000, v35
	s_waitcnt vmcnt(0)
; __device__ __forceinline__ void rms_row(const f32x4 (&v)[4], const float* g, int lane, float& rs, f32x4 (&y)[4]) {
;     float s = 0.f;
; #pragma unroll
;     for (int j = 0; j < 4; ++j) s += (v[j].x * v[j].x + v[j].y * v[j].y) + (v[j].z * v[j].z + v[j].w * v[j].w);
;     rs = __builtin_amdgcn_rsqf(wave_sum(s) * (1.f / DM) + EPS);
; #pragma unroll
;     for (int j = 0; j < 4; ++j) { const f32x4 gv = *((const f32x4*)g + lane + 64 * j); y[j] = v[j] * rs * gv; }
; }
; template <int NSLICE> __device__ __forceinline__ void rms_phase(ArgP a, const float* g, bool final_out, int G) {
;     ...
;         float rs; f32x4 y[4]; rms_row(v, g, lane, rs, y);
;         if (!final_out) store_bf16_row(XN + (size_t)m * DM, lane, y);
;         else { float* o = a->out + O_YS + (size_t)(m - R_SAMP) * DM;
; #pragma unroll
;             for (int j = 0; j < 4; ++j) *((f32x4*)o + lane + 64 * j) = y[j]; }
	v_lshlrev_b32_e32 v38, 16, v36
	v_and_b32_e32 v39, 0xffff0000, v36
	v_lshlrev_b32_e32 v40, 16, v37
	v_and_b32_e32 v41, 0xffff0000, v37
	v_pk_add_f32 v[36:37], v[24:25], v[26:27]
	v_pk_add_f32 v[6:7], v[6:7], v[44:45]
	v_pk_add_f32 v[26:27], v[22:23], v[30:31]
	v_pk_add_f32 v[28:29], v[8:9], v[28:29]
	v_pk_add_f32 v[8:9], v[10:11], v[34:35]
	v_pk_add_f32 v[10:11], v[4:5], v[32:33]
	v_pk_add_f32 v[22:23], v[2:3], v[38:39]
	v_pk_mul_f32 v[2:3], v[0:1], v[0:1]
	v_pk_mul_f32 v[4:5], v[36:37], v[36:37]
	v_pk_add_f32 v[20:21], v[6:7], v[40:41]
	v_pk_mov_b32 v[6:7], v[4:5], v[2:3] op_sel:[1,0]
	v_mov_b32_e32 v5, v3
	v_pk_add_f32 v[2:3], v[6:7], v[4:5]
	v_pk_mul_f32 v[4:5], v[28:29], v[28:29]
	v_pk_add_f32 v[2:3], v[2:3], v[2:3] op_sel_hi:[0,1]
	v_pk_mul_f32 v[6:7], v[26:27], v[26:27]
	v_mul_f32_e32 v2, v10, v10
	v_pk_mov_b32 v[24:25], v[6:7], v[4:5] op_sel:[1,0]
	v_mov_b32_e32 v7, v5
	v_pk_add_f32 v[4:5], v[24:25], v[6:7]
	v_pk_fma_f32 v[6:7], v[10:11], v[10:11], v[2:3] op_sel_hi:[1,1,0]
	v_mul_f32_e32 v2, v8, v8
	v_pk_add_f32 v[4:5], v[4:5], v[4:5] op_sel_hi:[0,1]
	v_pk_fma_f32 v[24:25], v[8:9], v[8:9], v[2:3] op_sel_hi:[1,1,0]
	v_mul_f32_e32 v6, v22, v22
	v_mul_f32_e32 v24, v23, v23
	v_mul_f32_e32 v2, v20, v20
	v_mul_f32_e32 v4, v21, v21
	v_pk_add_f32 v[6:7], v[6:7], v[24:25]
	v_pk_add_f32 v[2:3], v[2:3], v[4:5]
	v_xor_b32_e32 v4, 1, v208
	v_pk_add_f32 v[2:3], v[6:7], v[2:3]
	s_nop 0
	v_add_f32_e32 v2, v2, v3
	v_and_b32_e32 v3, 64, v208
	v_add_u32_e32 v3, 64, v3
	v_cmp_lt_i32_e32 vcc, v4, v3
	s_nop 1
	v_cndmask_b32_e32 v4, v208, v4, vcc
	v_lshlrev_b32_e32 v4, 2, v4
	ds_bpermute_b32 v4, v4, v2
	s_waitcnt lgkmcnt(0)
	v_add_f32_e32 v2, v2, v4
	v_xor_b32_e32 v4, 2, v208
	v_cmp_lt_i32_e32 vcc, v4, v3
	s_nop 1
	v_cndmask_b32_e32 v4, v208, v4, vcc
	v_lshlrev_b32_e32 v4, 2, v4
	ds_bpermute_b32 v4, v4, v2
	s_waitcnt lgkmcnt(0)
	v_add_f32_e32 v2, v2, v4
	v_xor_b32_e32 v4, 4, v208
	v_cmp_lt_i32_e32 vcc, v4, v3
	s_nop 1
	v_cndmask_b32_e32 v4, v208, v4, vcc
	v_lshlrev_b32_e32 v4, 2, v4
	ds_bpermute_b32 v4, v4, v2
	s_waitcnt lgkmcnt(0)
	v_add_f32_e32 v2, v2, v4
	v_xor_b32_e32 v4, 8, v208
	v_cmp_lt_i32_e32 vcc, v4, v3
	s_nop 1
	v_cndmask_b32_e32 v4, v208, v4, vcc
	v_lshlrev_b32_e32 v4, 2, v4
	ds_bpermute_b32 v4, v4, v2
	s_waitcnt lgkmcnt(0)
	v_add_f32_e32 v2, v2, v4
	v_xor_b32_e32 v4, 16, v208
	v_cmp_lt_i32_e32 vcc, v4, v3
	s_nop 1
	v_cndmask_b32_e32 v4, v208, v4, vcc
	v_lshlrev_b32_e32 v4, 2, v4
	ds_bpermute_b32 v4, v4, v2
	s_waitcnt lgkmcnt(0)
	v_add_f32_e32 v2, v2, v4
	v_xor_b32_e32 v4, 32, v208
	v_cmp_lt_i32_e32 vcc, v4, v3
	s_nop 1
	v_cndmask_b32_e32 v3, v208, v4, vcc
	global_load_dwordx4 v[4:7], v[16:17], off
	v_lshlrev_b32_e32 v3, 2, v3
	ds_bpermute_b32 v3, v3, v2
	s_waitcnt lgkmcnt(0)
	v_add_f32_e32 v2, v2, v3
	v_fmamk_f32 v2, v2, 0x3a800000, v207
	v_rsq_f32_e32 v24, v2
	s_nop 0
	v_pk_mul_f32 v[30:31], v[36:37], v[24:25] op_sel_hi:[1,0]
	v_pk_mul_f32 v[0:1], v[0:1], v[24:25] op_sel_hi:[1,0]
	v_pk_mul_f32 v[26:27], v[26:27], v[24:25] op_sel_hi:[1,0]
	v_pk_mul_f32 v[28:29], v[28:29], v[24:25] op_sel_hi:[1,0]
	v_pk_mul_f32 v[8:9], v[8:9], v[24:25] op_sel_hi:[1,0]
	v_pk_mul_f32 v[20:21], v[20:21], v[24:25] op_sel_hi:[1,0]
	s_waitcnt vmcnt(0)
	v_pk_mul_f32 v[2:3], v[6:7], v[0:1]
	v_pk_mul_f32 v[0:1], v[4:5], v[30:31]
	global_load_dwordx4 v[4:7], v[16:17], off offset:1024
	v_pk_mul_f32 v[30:31], v[10:11], v[24:25] op_sel_hi:[1,0]
	s_waitcnt vmcnt(0)
	v_pk_mul_f32 v[6:7], v[6:7], v[28:29]
	v_pk_mul_f32 v[4:5], v[4:5], v[26:27]
	global_load_dwordx4 v[26:29], v[16:17], off offset:2048
	s_waitcnt vmcnt(0)
	v_pk_mul_f32 v[10:11], v[28:29], v[8:9]
	v_pk_mul_f32 v[8:9], v[26:27], v[30:31]
	global_load_dwordx4 v[26:29], v[16:17], off offset:3072
	v_pk_mul_f32 v[30:31], v[22:23], v[24:25] op_sel_hi:[1,0]
	v_add_u32_e32 v24, 0xffffbf80, v188
	v_mov_b32_e32 v25, v189
	v_lshlrev_b64 v[24:25], 12, v[24:25]
	v_lshl_add_u64 v[24:25], s[10:11], 0, v[24:25]
	v_lshl_add_u64 v[24:25], v[24:25], 0, v[18:19]
	s_mov_b64 s[10:11], 0x4000000
	s_waitcnt vmcnt(0)
	v_pk_mul_f32 v[22:23], v[28:29], v[20:21]
	v_pk_mul_f32 v[20:21], v[26:27], v[30:31]
	v_lshl_add_u64 v[26:27], v[24:25], 0, s[10:11]
	v_add_co_u32_e32 v24, vcc, 0x4000000, v24
	s_nop 1
	v_addc_co_u32_e32 v25, vcc, 0, v25, vcc
	global_store_dwordx4 v[24:25], v[0:3], off nt
	global_store_dwordx4 v[26:27], v[4:7], off offset:1024 nt
	global_store_dwordx4 v[26:27], v[8:11], off offset:2048 nt
	global_store_dwordx4 v[26:27], v[20:23], off offset:3072 nt
	s_branch .LBB0_1327
